# GEMM K-loops: 4 of the 6 LDS-DMA issues of each SP2 load segment moved into the following MFMA segment, SP2 waits re-derived as vmcnt(4) (on top of v5)
# baseline (speedup 1.0000x reference)
.LBB0_259:
	s_add_u32 s24, s22, 0xfffc0080
	s_addc_u32 s25, s23, -1
	s_add_i32 s42, 0, 0x10000
	s_cmp_eq_u32 s41, 12
	s_cselect_b32 s27, s0, s25
	s_cselect_b32 s26, s1, s24
	s_cselect_b32 s25, s7, s40
	s_cselect_b32 s24, s9, s37
	s_add_i32 s44, 0, 0x14000
	v_add_u32_e32 v156, s42, v145
	v_add_u32_e32 v172, s44, v145
	ds_read_b128 v[140:143], v156
	ds_read_b128 v[148:151], v156 offset:1024
	ds_read_b128 v[152:155], v156 offset:2048
	ds_read_b128 v[156:159], v156 offset:3072
	ds_read_b128 v[160:163], v172
	ds_read_b128 v[164:167], v172 offset:1024
	ds_read_b128 v[168:171], v172 offset:2048
	ds_read_b128 v[172:175], v172 offset:3072
	v_lshl_add_u64 v[180:181], s[22:23], 0, v[136:137]
	s_add_i32 m0, s13, 0xc000
	ds_read_b128 v[176:179], v147
	ds_read_b128 v[186:189], v147 offset:1024
	ds_read_b128 v[190:193], v147 offset:2048
	ds_read_b128 v[194:197], v147 offset:3072
	ds_read_b128 v[214:217], v147 offset:4096
	ds_read_b128 v[218:221], v147 offset:5120
	ds_read_b128 v[222:225], v147 offset:6144
	ds_read_b128 v[226:229], v147 offset:7168
	global_load_lds_dwordx4 v[180:181], off
	v_lshl_add_u64 v[180:181], s[22:23], 0, v[138:139]
	s_add_i32 m0, s13, 0xe000
	s_nop 0
	global_load_lds_dwordx4 v[180:181], off
	s_waitcnt vmcnt(8)
	s_waitcnt lgkmcnt(0)
	s_barrier
	s_setprio 1
	s_waitcnt lgkmcnt(0)
	v_mfma_f32_16x16x32_bf16 v[126:129], v[140:143], v[176:179], v[126:129]
	v_mfma_f32_16x16x32_bf16 v[122:125], v[152:155], v[176:179], v[122:125]
	v_mfma_f32_16x16x32_bf16 v[118:121], v[140:143], v[190:193], v[118:121]
	v_mfma_f32_16x16x32_bf16 v[110:113], v[152:155], v[190:193], v[110:113]
	v_mfma_f32_16x16x32_bf16 v[102:105], v[140:143], v[214:217], v[102:105]
	v_mfma_f32_16x16x32_bf16 v[94:97], v[152:155], v[214:217], v[94:97]
	v_mfma_f32_16x16x32_bf16 v[86:89], v[140:143], v[222:225], v[86:89]
	v_mfma_f32_16x16x32_bf16 v[78:81], v[152:155], v[222:225], v[78:81]
	v_mfma_f32_16x16x32_bf16 v[126:129], v[148:151], v[186:189], v[126:129]
	v_mfma_f32_16x16x32_bf16 v[122:125], v[156:159], v[186:189], v[122:125]
	v_mfma_f32_16x16x32_bf16 v[118:121], v[148:151], v[194:197], v[118:121]
	v_mfma_f32_16x16x32_bf16 v[110:113], v[156:159], v[194:197], v[110:113]
	v_mfma_f32_16x16x32_bf16 v[102:105], v[148:151], v[218:221], v[102:105]
	v_mfma_f32_16x16x32_bf16 v[94:97], v[156:159], v[218:221], v[94:97]
	v_mfma_f32_16x16x32_bf16 v[86:89], v[148:151], v[226:229], v[86:89]
	v_mfma_f32_16x16x32_bf16 v[78:81], v[156:159], v[226:229], v[78:81]
	s_setprio 0
	s_setprio 1
	v_mfma_f32_16x16x32_bf16 v[114:117], v[160:163], v[176:179], v[114:117]
	v_mfma_f32_16x16x32_bf16 v[106:109], v[168:171], v[176:179], v[106:109]
	v_mfma_f32_16x16x32_bf16 v[98:101], v[160:163], v[190:193], v[98:101]
	v_mfma_f32_16x16x32_bf16 v[90:93], v[168:171], v[190:193], v[90:93]
	v_mfma_f32_16x16x32_bf16 v[82:85], v[160:163], v[214:217], v[82:85]
	v_mfma_f32_16x16x32_bf16 v[74:77], v[168:171], v[214:217], v[74:77]
	v_mfma_f32_16x16x32_bf16 v[70:73], v[160:163], v[222:225], v[70:73]
	v_mfma_f32_16x16x32_bf16 v[66:69], v[168:171], v[222:225], v[66:69]
	v_mfma_f32_16x16x32_bf16 v[114:117], v[164:167], v[186:189], v[114:117]
	v_mfma_f32_16x16x32_bf16 v[106:109], v[172:175], v[186:189], v[106:109]
	v_mfma_f32_16x16x32_bf16 v[98:101], v[164:167], v[194:197], v[98:101]
	v_mfma_f32_16x16x32_bf16 v[90:93], v[172:175], v[194:197], v[90:93]
	v_mfma_f32_16x16x32_bf16 v[82:85], v[164:167], v[218:221], v[82:85]
	v_mfma_f32_16x16x32_bf16 v[74:77], v[172:175], v[218:221], v[74:77]
	v_mfma_f32_16x16x32_bf16 v[70:73], v[164:167], v[226:229], v[70:73]
	v_mfma_f32_16x16x32_bf16 v[66:69], v[172:175], v[226:229], v[66:69]
	s_setprio 0
	s_barrier
	s_add_i32 s42, s42, s12
	v_lshl_add_u64 v[180:181], s[24:25], 0, v[0:1]
	s_mov_b32 m0, s42
	ds_read_b128 v[176:179], v147 offset:16384
	ds_read_b128 v[186:189], v147 offset:17408
	ds_read_b128 v[190:193], v147 offset:18432
	ds_read_b128 v[194:197], v147 offset:19456
	ds_read_b128 v[214:217], v147 offset:20480
	ds_read_b128 v[218:221], v147 offset:21504
	ds_read_b128 v[222:225], v147 offset:22528
	ds_read_b128 v[226:229], v147 offset:23552
	global_load_lds_dwordx4 v[180:181], off
	s_add_i32 m0, s42, 0x2000
	s_add_u32 s42, s24, 0x40000
	v_lshl_add_u64 v[230:231], s[24:25], 0, v[130:131]
	s_addc_u32 s43, s25, 0
	s_add_i32 s44, s44, s12
	global_load_lds_dwordx4 v[230:231], off
	s_waitcnt vmcnt(4)
	s_waitcnt lgkmcnt(0)
	s_barrier
	s_setprio 1
	s_waitcnt lgkmcnt(0)
	v_mfma_f32_16x16x32_bf16 v[62:65], v[140:143], v[176:179], v[62:65]
	v_mfma_f32_16x16x32_bf16 v[58:61], v[152:155], v[176:179], v[58:61]
	v_mfma_f32_16x16x32_bf16 v[54:57], v[140:143], v[190:193], v[54:57]
	v_mfma_f32_16x16x32_bf16 v[46:49], v[152:155], v[190:193], v[46:49]
	v_lshl_add_u64 v[232:233], s[42:43], 0, v[0:1]
	s_mov_b32 m0, s44
	v_lshl_add_u64 v[234:235], s[26:27], 0, v[132:133]
	global_load_lds_dwordx4 v[232:233], off
	v_mfma_f32_16x16x32_bf16 v[38:41], v[140:143], v[214:217], v[38:41]
	v_mfma_f32_16x16x32_bf16 v[30:33], v[152:155], v[214:217], v[30:33]
	v_mfma_f32_16x16x32_bf16 v[22:25], v[140:143], v[222:225], v[22:25]
	v_mfma_f32_16x16x32_bf16 v[14:17], v[152:155], v[222:225], v[14:17]
	v_mfma_f32_16x16x32_bf16 v[62:65], v[148:151], v[186:189], v[62:65]
	v_mfma_f32_16x16x32_bf16 v[58:61], v[156:159], v[186:189], v[58:61]
	v_mfma_f32_16x16x32_bf16 v[54:57], v[148:151], v[194:197], v[54:57]
	v_mfma_f32_16x16x32_bf16 v[46:49], v[156:159], v[194:197], v[46:49]
	v_lshl_add_u64 v[232:233], s[42:43], 0, v[130:131]
	s_add_i32 m0, s44, 0x2000
	s_nop 0
	global_load_lds_dwordx4 v[232:233], off
	v_mfma_f32_16x16x32_bf16 v[38:41], v[148:151], v[218:221], v[38:41]
	v_mfma_f32_16x16x32_bf16 v[30:33], v[156:159], v[218:221], v[30:33]
	v_mfma_f32_16x16x32_bf16 v[22:25], v[148:151], v[226:229], v[22:25]
	v_mfma_f32_16x16x32_bf16 v[14:17], v[156:159], v[226:229], v[14:17]
	s_setprio 0
	s_setprio 1
	v_mfma_f32_16x16x32_bf16 v[50:53], v[160:163], v[176:179], v[50:53]
	v_mfma_f32_16x16x32_bf16 v[42:45], v[168:171], v[176:179], v[42:45]
	v_mfma_f32_16x16x32_bf16 v[34:37], v[160:163], v[190:193], v[34:37]
	v_mfma_f32_16x16x32_bf16 v[26:29], v[168:171], v[190:193], v[26:29]
	v_lshl_add_u64 v[232:233], s[26:27], 0, v[134:135]
	s_mov_b32 m0, s13
	s_nop 0
	global_load_lds_dwordx4 v[232:233], off
	v_mfma_f32_16x16x32_bf16 v[18:21], v[160:163], v[214:217], v[18:21]
	v_mfma_f32_16x16x32_bf16 v[10:13], v[168:171], v[214:217], v[10:13]
	v_mfma_f32_16x16x32_bf16 v[6:9], v[160:163], v[222:225], v[6:9]
	v_mfma_f32_16x16x32_bf16 v[2:5], v[168:171], v[222:225], v[2:5]
	v_mfma_f32_16x16x32_bf16 v[50:53], v[164:167], v[186:189], v[50:53]
	v_mfma_f32_16x16x32_bf16 v[42:45], v[172:175], v[186:189], v[42:45]
	v_mfma_f32_16x16x32_bf16 v[34:37], v[164:167], v[194:197], v[34:37]
	v_mfma_f32_16x16x32_bf16 v[26:29], v[172:175], v[194:197], v[26:29]
	s_mov_b32 m0, s14
	s_nop 0
	global_load_lds_dwordx4 v[234:235], off
	v_mfma_f32_16x16x32_bf16 v[18:21], v[164:167], v[218:221], v[18:21]
	v_mfma_f32_16x16x32_bf16 v[10:13], v[172:175], v[218:221], v[10:13]
	v_mfma_f32_16x16x32_bf16 v[6:9], v[164:167], v[226:229], v[6:9]
	v_mfma_f32_16x16x32_bf16 v[2:5], v[172:175], v[226:229], v[2:5]
	s_setprio 0
	s_barrier
	s_add_i32 s42, 0, 0x18000
	s_add_i32 s43, 0, 0x1c000
	v_add_u32_e32 v156, s42, v145
	v_add_u32_e32 v172, s43, v145
	ds_read_b128 v[140:143], v156
	ds_read_b128 v[148:151], v156 offset:1024
	ds_read_b128 v[152:155], v156 offset:2048
	ds_read_b128 v[156:159], v156 offset:3072
	ds_read_b128 v[160:163], v172
	ds_read_b128 v[164:167], v172 offset:1024
	ds_read_b128 v[168:171], v172 offset:2048
	ds_read_b128 v[172:175], v172 offset:3072
	s_add_u32 s26, s26, 0x40000
	s_addc_u32 s27, s27, 0
	s_mov_b32 m0, s28
	v_lshl_add_u64 v[240:241], s[26:27], 0, v[134:135]
	ds_read_b128 v[176:179], v147 offset:32768
	ds_read_b128 v[186:189], v147 offset:33792
	ds_read_b128 v[190:193], v147 offset:34816
	ds_read_b128 v[194:197], v147 offset:35840
	ds_read_b128 v[214:217], v147 offset:36864
	ds_read_b128 v[218:221], v147 offset:37888
	ds_read_b128 v[222:225], v147 offset:38912
	ds_read_b128 v[226:229], v147 offset:39936
	global_load_lds_dwordx4 v[240:241], off
	v_lshl_add_u64 v[240:241], s[26:27], 0, v[132:133]
	s_mov_b32 m0, s29
	s_nop 0
	global_load_lds_dwordx4 v[240:241], off
	s_waitcnt vmcnt(8)
	s_waitcnt lgkmcnt(0)
	s_barrier
	s_setprio 1
	s_waitcnt lgkmcnt(0)
	v_mfma_f32_16x16x32_bf16 v[126:129], v[140:143], v[176:179], v[126:129]
	v_mfma_f32_16x16x32_bf16 v[122:125], v[152:155], v[176:179], v[122:125]
	v_mfma_f32_16x16x32_bf16 v[118:121], v[140:143], v[190:193], v[118:121]
	v_mfma_f32_16x16x32_bf16 v[110:113], v[152:155], v[190:193], v[110:113]
	v_mfma_f32_16x16x32_bf16 v[102:105], v[140:143], v[214:217], v[102:105]
	v_mfma_f32_16x16x32_bf16 v[94:97], v[152:155], v[214:217], v[94:97]
	v_mfma_f32_16x16x32_bf16 v[86:89], v[140:143], v[222:225], v[86:89]
	v_mfma_f32_16x16x32_bf16 v[78:81], v[152:155], v[222:225], v[78:81]
	v_mfma_f32_16x16x32_bf16 v[126:129], v[148:151], v[186:189], v[126:129]
	v_mfma_f32_16x16x32_bf16 v[122:125], v[156:159], v[186:189], v[122:125]
	v_mfma_f32_16x16x32_bf16 v[118:121], v[148:151], v[194:197], v[118:121]
	v_mfma_f32_16x16x32_bf16 v[110:113], v[156:159], v[194:197], v[110:113]
	v_mfma_f32_16x16x32_bf16 v[102:105], v[148:151], v[218:221], v[102:105]
	v_mfma_f32_16x16x32_bf16 v[94:97], v[156:159], v[218:221], v[94:97]
	v_mfma_f32_16x16x32_bf16 v[86:89], v[148:151], v[226:229], v[86:89]
	v_mfma_f32_16x16x32_bf16 v[78:81], v[156:159], v[226:229], v[78:81]
	s_setprio 0
	s_setprio 1
	v_mfma_f32_16x16x32_bf16 v[114:117], v[160:163], v[176:179], v[114:117]
	v_mfma_f32_16x16x32_bf16 v[106:109], v[168:171], v[176:179], v[106:109]
	v_mfma_f32_16x16x32_bf16 v[98:101], v[160:163], v[190:193], v[98:101]
	v_mfma_f32_16x16x32_bf16 v[90:93], v[168:171], v[190:193], v[90:93]
	v_mfma_f32_16x16x32_bf16 v[82:85], v[160:163], v[214:217], v[82:85]
	v_mfma_f32_16x16x32_bf16 v[74:77], v[168:171], v[214:217], v[74:77]
	v_mfma_f32_16x16x32_bf16 v[70:73], v[160:163], v[222:225], v[70:73]
	v_mfma_f32_16x16x32_bf16 v[66:69], v[168:171], v[222:225], v[66:69]
	v_mfma_f32_16x16x32_bf16 v[114:117], v[164:167], v[186:189], v[114:117]
	v_mfma_f32_16x16x32_bf16 v[106:109], v[172:175], v[186:189], v[106:109]
	v_mfma_f32_16x16x32_bf16 v[98:101], v[164:167], v[194:197], v[98:101]
	v_mfma_f32_16x16x32_bf16 v[90:93], v[172:175], v[194:197], v[90:93]
	v_mfma_f32_16x16x32_bf16 v[82:85], v[164:167], v[218:221], v[82:85]
	v_mfma_f32_16x16x32_bf16 v[74:77], v[172:175], v[218:221], v[74:77]
	v_mfma_f32_16x16x32_bf16 v[70:73], v[164:167], v[226:229], v[70:73]
	v_mfma_f32_16x16x32_bf16 v[66:69], v[172:175], v[226:229], v[66:69]
	s_setprio 0
	s_barrier
	s_add_i32 s26, s42, s12
	v_lshl_add_u64 v[180:181], v[180:181], 0, s[54:55]
	s_mov_b32 m0, s26
	ds_read_b128 v[176:179], v147 offset:49152
	ds_read_b128 v[186:189], v147 offset:50176
	ds_read_b128 v[190:193], v147 offset:51200
	ds_read_b128 v[194:197], v147 offset:52224
	ds_read_b128 v[214:217], v147 offset:53248
	ds_read_b128 v[218:221], v147 offset:54272
	ds_read_b128 v[222:225], v147 offset:55296
	ds_read_b128 v[226:229], v147 offset:56320
	global_load_lds_dwordx4 v[180:181], off
	s_add_i32 m0, s26, 0x2000
	s_add_u32 s24, s24, 0x40080
	v_lshl_add_u64 v[180:181], v[230:231], 0, s[54:55]
	s_addc_u32 s25, s25, 0
	s_add_i32 s26, s43, s12
	global_load_lds_dwordx4 v[180:181], off
	s_waitcnt vmcnt(4)
	s_waitcnt lgkmcnt(0)
	s_barrier
	s_setprio 1
	s_waitcnt lgkmcnt(0)
	v_mfma_f32_16x16x32_bf16 v[62:65], v[140:143], v[176:179], v[62:65]
	v_mfma_f32_16x16x32_bf16 v[58:61], v[152:155], v[176:179], v[58:61]
	v_mfma_f32_16x16x32_bf16 v[54:57], v[140:143], v[190:193], v[54:57]
	v_mfma_f32_16x16x32_bf16 v[46:49], v[152:155], v[190:193], v[46:49]
	v_lshl_add_u64 v[180:181], s[24:25], 0, v[0:1]
	s_mov_b32 m0, s26
	s_nop 0
	global_load_lds_dwordx4 v[180:181], off
	v_mfma_f32_16x16x32_bf16 v[38:41], v[140:143], v[214:217], v[38:41]
	v_mfma_f32_16x16x32_bf16 v[30:33], v[152:155], v[214:217], v[30:33]
	v_mfma_f32_16x16x32_bf16 v[22:25], v[140:143], v[222:225], v[22:25]
	v_mfma_f32_16x16x32_bf16 v[14:17], v[152:155], v[222:225], v[14:17]
	v_mfma_f32_16x16x32_bf16 v[62:65], v[148:151], v[186:189], v[62:65]
	v_mfma_f32_16x16x32_bf16 v[58:61], v[156:159], v[186:189], v[58:61]
	v_mfma_f32_16x16x32_bf16 v[54:57], v[148:151], v[194:197], v[54:57]
	v_mfma_f32_16x16x32_bf16 v[46:49], v[156:159], v[194:197], v[46:49]
	v_lshl_add_u64 v[180:181], s[24:25], 0, v[130:131]
	s_add_i32 m0, s26, 0x2000
	s_nop 0
	global_load_lds_dwordx4 v[180:181], off
	v_mfma_f32_16x16x32_bf16 v[38:41], v[148:151], v[218:221], v[38:41]
	v_mfma_f32_16x16x32_bf16 v[30:33], v[156:159], v[218:221], v[30:33]
	v_mfma_f32_16x16x32_bf16 v[22:25], v[148:151], v[226:229], v[22:25]
	v_mfma_f32_16x16x32_bf16 v[14:17], v[156:159], v[226:229], v[14:17]
	s_setprio 0
	s_setprio 1
	v_mfma_f32_16x16x32_bf16 v[50:53], v[160:163], v[176:179], v[50:53]
	v_mfma_f32_16x16x32_bf16 v[42:45], v[168:171], v[176:179], v[42:45]
	v_mfma_f32_16x16x32_bf16 v[34:37], v[160:163], v[190:193], v[34:37]
	v_mfma_f32_16x16x32_bf16 v[26:29], v[168:171], v[190:193], v[26:29]
	v_lshl_add_u64 v[180:181], v[232:233], 0, s[54:55]
	s_mov_b32 m0, s30
	s_nop 0
	global_load_lds_dwordx4 v[180:181], off
	v_mfma_f32_16x16x32_bf16 v[18:21], v[160:163], v[214:217], v[18:21]
	v_mfma_f32_16x16x32_bf16 v[10:13], v[168:171], v[214:217], v[10:13]
	v_mfma_f32_16x16x32_bf16 v[6:9], v[160:163], v[222:225], v[6:9]
	v_mfma_f32_16x16x32_bf16 v[2:5], v[168:171], v[222:225], v[2:5]
	v_mfma_f32_16x16x32_bf16 v[50:53], v[164:167], v[186:189], v[50:53]
	v_mfma_f32_16x16x32_bf16 v[42:45], v[172:175], v[186:189], v[42:45]
	v_mfma_f32_16x16x32_bf16 v[34:37], v[164:167], v[194:197], v[34:37]
	v_mfma_f32_16x16x32_bf16 v[26:29], v[172:175], v[194:197], v[26:29]
	v_lshl_add_u64 v[180:181], v[234:235], 0, s[54:55]
	s_mov_b32 m0, s31
	s_nop 0
	global_load_lds_dwordx4 v[180:181], off
	v_mfma_f32_16x16x32_bf16 v[18:21], v[164:167], v[218:221], v[18:21]
	v_mfma_f32_16x16x32_bf16 v[10:13], v[172:175], v[218:221], v[10:13]
	v_mfma_f32_16x16x32_bf16 v[6:9], v[164:167], v[226:229], v[6:9]
	v_mfma_f32_16x16x32_bf16 v[2:5], v[172:175], v[226:229], v[2:5]
	s_setprio 0
	s_barrier
	s_add_i32 s41, s41, 2
	s_add_u32 s22, s22, 0x100
	s_addc_u32 s23, s23, 0
	s_add_u32 s37, s37, 0x100
	s_addc_u32 s40, s40, 0
	s_cmp_gt_u32 s41, 13
	s_cbranch_scc0 .LBB0_259
	s_and_b64 vcc, exec, s[4:5]
	s_cbranch_vccz .LBB0_262
	s_barrier

.LBB0_1022:
	s_add_u32 s16, s2, 0x100
	s_addc_u32 s17, s3, 0
	s_add_i32 s18, 0, 0x10000
	s_cmp_eq_u32 s37, 12
	s_cselect_b32 s25, s0, s17
	s_cselect_b32 s24, s1, s16
	v_add_u32_e32 v159, s18, v156
	s_cselect_b32 s23, s5, s36
	s_cselect_b32 s22, s7, s35
	s_add_i32 s19, 0, 0x14000
	ds_read_b128 v[152:155], v159
	ds_read_b128 v[160:163], v159 offset:1024
	ds_read_b128 v[164:167], v159 offset:2048
	ds_read_b128 v[168:171], v159 offset:3072
	v_add_u32_e32 v159, s19, v156
	ds_read_b128 v[172:175], v159
	ds_read_b128 v[176:179], v159 offset:1024
	ds_read_b128 v[186:189], v159 offset:2048
	ds_read_b128 v[190:193], v159 offset:3072
	v_lshl_add_u64 v[180:181], s[2:3], 0, v[148:149]
	s_add_i32 m0, s26, 0xc000
	ds_read_b128 v[194:197], v158
	ds_read_b128 v[214:217], v158 offset:1024
	ds_read_b128 v[218:221], v158 offset:2048
	ds_read_b128 v[222:225], v158 offset:3072
	ds_read_b128 v[226:229], v158 offset:4096
	ds_read_b128 v[230:233], v158 offset:5120
	ds_read_b128 v[240:243], v158 offset:6144
	ds_read_b128 v[244:247], v158 offset:7168
	global_load_lds_dwordx4 v[180:181], off
	v_lshl_add_u64 v[180:181], s[2:3], 0, v[150:151]
	s_add_i32 m0, s26, 0xe000
	s_nop 0
	global_load_lds_dwordx4 v[180:181], off
	s_waitcnt vmcnt(8)
	s_waitcnt lgkmcnt(0)
	s_barrier
	s_setprio 1
	s_waitcnt lgkmcnt(0)
	v_mfma_f32_16x16x32_bf16 v[126:129], v[152:155], v[194:197], v[126:129]
	v_mfma_f32_16x16x32_bf16 v[102:105], v[164:167], v[194:197], v[102:105]
	v_mfma_f32_16x16x32_bf16 v[122:125], v[152:155], v[218:221], v[122:125]
	v_mfma_f32_16x16x32_bf16 v[90:93], v[164:167], v[218:221], v[90:93]
	v_mfma_f32_16x16x32_bf16 v[118:121], v[152:155], v[226:229], v[118:121]
	v_mfma_f32_16x16x32_bf16 v[86:89], v[164:167], v[226:229], v[86:89]
	v_mfma_f32_16x16x32_bf16 v[114:117], v[152:155], v[240:243], v[114:117]
	v_mfma_f32_16x16x32_bf16 v[82:85], v[164:167], v[240:243], v[82:85]
	v_mfma_f32_16x16x32_bf16 v[126:129], v[160:163], v[214:217], v[126:129]
	v_mfma_f32_16x16x32_bf16 v[102:105], v[168:171], v[214:217], v[102:105]
	v_mfma_f32_16x16x32_bf16 v[122:125], v[160:163], v[222:225], v[122:125]
	v_mfma_f32_16x16x32_bf16 v[90:93], v[168:171], v[222:225], v[90:93]
	v_mfma_f32_16x16x32_bf16 v[118:121], v[160:163], v[230:233], v[118:121]
	v_mfma_f32_16x16x32_bf16 v[86:89], v[168:171], v[230:233], v[86:89]
	v_mfma_f32_16x16x32_bf16 v[114:117], v[160:163], v[244:247], v[114:117]
	v_mfma_f32_16x16x32_bf16 v[82:85], v[168:171], v[244:247], v[82:85]
	s_setprio 0
	s_setprio 1
	v_mfma_f32_16x16x32_bf16 v[62:65], v[172:175], v[194:197], v[62:65]
	v_mfma_f32_16x16x32_bf16 v[38:41], v[186:189], v[194:197], v[38:41]
	v_mfma_f32_16x16x32_bf16 v[58:61], v[172:175], v[218:221], v[58:61]
	v_mfma_f32_16x16x32_bf16 v[26:29], v[186:189], v[218:221], v[26:29]
	v_mfma_f32_16x16x32_bf16 v[54:57], v[172:175], v[226:229], v[54:57]
	v_mfma_f32_16x16x32_bf16 v[22:25], v[186:189], v[226:229], v[22:25]
	v_mfma_f32_16x16x32_bf16 v[50:53], v[172:175], v[240:243], v[50:53]
	v_mfma_f32_16x16x32_bf16 v[18:21], v[186:189], v[240:243], v[18:21]
	v_mfma_f32_16x16x32_bf16 v[62:65], v[176:179], v[214:217], v[62:65]
	v_mfma_f32_16x16x32_bf16 v[38:41], v[190:193], v[214:217], v[38:41]
	v_mfma_f32_16x16x32_bf16 v[58:61], v[176:179], v[222:225], v[58:61]
	v_mfma_f32_16x16x32_bf16 v[26:29], v[190:193], v[222:225], v[26:29]
	v_mfma_f32_16x16x32_bf16 v[54:57], v[176:179], v[230:233], v[54:57]
	v_mfma_f32_16x16x32_bf16 v[22:25], v[190:193], v[230:233], v[22:25]
	v_mfma_f32_16x16x32_bf16 v[50:53], v[176:179], v[244:247], v[50:53]
	v_mfma_f32_16x16x32_bf16 v[18:21], v[190:193], v[244:247], v[18:21]
	s_setprio 0
	s_barrier
	s_add_i32 s2, s18, s14
	v_lshl_add_u64 v[180:181], s[22:23], 0, v[0:1]
	s_mov_b32 m0, s2
	ds_read_b128 v[194:197], v158 offset:16384
	ds_read_b128 v[214:217], v158 offset:17408
	ds_read_b128 v[218:221], v158 offset:18432
	ds_read_b128 v[222:225], v158 offset:19456
	ds_read_b128 v[226:229], v158 offset:20480
	ds_read_b128 v[230:233], v158 offset:21504
	ds_read_b128 v[240:243], v158 offset:22528
	ds_read_b128 v[244:247], v158 offset:23552
	global_load_lds_dwordx4 v[180:181], off
	s_add_i32 m0, s2, 0x2000
	s_add_u32 s2, s22, 0x40000
	v_lshl_add_u64 v[234:235], s[22:23], 0, v[130:131]
	s_addc_u32 s3, s23, 0
	s_add_i32 s18, s19, s14
	global_load_lds_dwordx4 v[234:235], off
	s_waitcnt vmcnt(4)
	s_waitcnt lgkmcnt(0)
	s_barrier
	s_setprio 1
	s_waitcnt lgkmcnt(0)
	v_mfma_f32_16x16x32_bf16 v[110:113], v[152:155], v[194:197], v[110:113]
	v_mfma_f32_16x16x32_bf16 v[78:81], v[164:167], v[194:197], v[78:81]
	v_mfma_f32_16x16x32_bf16 v[106:109], v[152:155], v[218:221], v[106:109]
	v_mfma_f32_16x16x32_bf16 v[74:77], v[164:167], v[218:221], v[74:77]
	v_lshl_add_u64 v[210:211], s[2:3], 0, v[0:1]
	s_mov_b32 m0, s18
	v_lshl_add_u64 v[182:183], s[24:25], 0, v[130:131]
	global_load_lds_dwordx4 v[210:211], off
	v_mfma_f32_16x16x32_bf16 v[98:101], v[152:155], v[226:229], v[98:101]
	v_mfma_f32_16x16x32_bf16 v[70:73], v[164:167], v[226:229], v[70:73]
	v_mfma_f32_16x16x32_bf16 v[94:97], v[152:155], v[240:243], v[94:97]
	v_mfma_f32_16x16x32_bf16 v[66:69], v[164:167], v[240:243], v[66:69]
	v_mfma_f32_16x16x32_bf16 v[110:113], v[160:163], v[214:217], v[110:113]
	v_mfma_f32_16x16x32_bf16 v[78:81], v[168:171], v[214:217], v[78:81]
	v_mfma_f32_16x16x32_bf16 v[106:109], v[160:163], v[222:225], v[106:109]
	v_mfma_f32_16x16x32_bf16 v[74:77], v[168:171], v[222:225], v[74:77]
	v_lshl_add_u64 v[210:211], s[2:3], 0, v[130:131]
	s_add_i32 m0, s18, 0x2000
	s_nop 0
	global_load_lds_dwordx4 v[210:211], off
	v_mfma_f32_16x16x32_bf16 v[98:101], v[160:163], v[230:233], v[98:101]
	v_mfma_f32_16x16x32_bf16 v[70:73], v[168:171], v[230:233], v[70:73]
	v_mfma_f32_16x16x32_bf16 v[94:97], v[160:163], v[244:247], v[94:97]
	v_mfma_f32_16x16x32_bf16 v[66:69], v[168:171], v[244:247], v[66:69]
	s_setprio 0
	s_setprio 1
	v_mfma_f32_16x16x32_bf16 v[46:49], v[172:175], v[194:197], v[46:49]
	v_mfma_f32_16x16x32_bf16 v[14:17], v[186:189], v[194:197], v[14:17]
	v_mfma_f32_16x16x32_bf16 v[42:45], v[172:175], v[218:221], v[42:45]
	v_mfma_f32_16x16x32_bf16 v[10:13], v[186:189], v[218:221], v[10:13]
	v_lshl_add_u64 v[210:211], s[24:25], 0, v[0:1]
	s_mov_b32 m0, s26
	s_nop 0
	global_load_lds_dwordx4 v[210:211], off
	v_mfma_f32_16x16x32_bf16 v[34:37], v[172:175], v[226:229], v[34:37]
	v_mfma_f32_16x16x32_bf16 v[6:9], v[186:189], v[226:229], v[6:9]
	v_mfma_f32_16x16x32_bf16 v[30:33], v[172:175], v[240:243], v[30:33]
	v_mfma_f32_16x16x32_bf16 v[2:5], v[186:189], v[240:243], v[2:5]
	v_mfma_f32_16x16x32_bf16 v[46:49], v[176:179], v[214:217], v[46:49]
	v_mfma_f32_16x16x32_bf16 v[14:17], v[190:193], v[214:217], v[14:17]
	v_mfma_f32_16x16x32_bf16 v[42:45], v[176:179], v[222:225], v[42:45]
	v_mfma_f32_16x16x32_bf16 v[10:13], v[190:193], v[222:225], v[10:13]
	s_mov_b32 m0, s27
	s_nop 0
	global_load_lds_dwordx4 v[182:183], off
	v_mfma_f32_16x16x32_bf16 v[34:37], v[176:179], v[230:233], v[34:37]
	v_mfma_f32_16x16x32_bf16 v[6:9], v[190:193], v[230:233], v[6:9]
	v_mfma_f32_16x16x32_bf16 v[30:33], v[176:179], v[244:247], v[30:33]
	v_mfma_f32_16x16x32_bf16 v[2:5], v[190:193], v[244:247], v[2:5]
	s_setprio 0
	s_barrier
	s_add_i32 s18, 0, 0x18000
	v_add_u32_e32 v159, s18, v156
	s_add_i32 s19, 0, 0x1c000
	ds_read_b128 v[152:155], v159
	ds_read_b128 v[160:163], v159 offset:1024
	ds_read_b128 v[164:167], v159 offset:2048
	ds_read_b128 v[168:171], v159 offset:3072
	v_add_u32_e32 v159, s19, v156
	ds_read_b128 v[172:175], v159
	ds_read_b128 v[176:179], v159 offset:1024
	ds_read_b128 v[186:189], v159 offset:2048
	ds_read_b128 v[190:193], v159 offset:3072
	s_add_u32 s2, s24, 0x40000
	s_addc_u32 s3, s25, 0
	s_mov_b32 m0, s28
	v_lshl_add_u64 v[184:185], s[2:3], 0, v[0:1]
	ds_read_b128 v[194:197], v158 offset:32768
	ds_read_b128 v[214:217], v158 offset:33792
	ds_read_b128 v[218:221], v158 offset:34816
	ds_read_b128 v[222:225], v158 offset:35840
	ds_read_b128 v[226:229], v158 offset:36864
	ds_read_b128 v[230:233], v158 offset:37888
	ds_read_b128 v[240:243], v158 offset:38912
	ds_read_b128 v[244:247], v158 offset:39936
	global_load_lds_dwordx4 v[184:185], off
	v_lshl_add_u64 v[184:185], s[2:3], 0, v[130:131]
	s_mov_b32 m0, s29
	s_nop 0
	global_load_lds_dwordx4 v[184:185], off
	s_waitcnt vmcnt(8)
	s_waitcnt lgkmcnt(0)
	s_barrier
	s_setprio 1
	s_waitcnt lgkmcnt(0)
	v_mfma_f32_16x16x32_bf16 v[126:129], v[152:155], v[194:197], v[126:129]
	v_mfma_f32_16x16x32_bf16 v[102:105], v[164:167], v[194:197], v[102:105]
	v_mfma_f32_16x16x32_bf16 v[122:125], v[152:155], v[218:221], v[122:125]
	v_mfma_f32_16x16x32_bf16 v[90:93], v[164:167], v[218:221], v[90:93]
	v_mfma_f32_16x16x32_bf16 v[118:121], v[152:155], v[226:229], v[118:121]
	v_mfma_f32_16x16x32_bf16 v[86:89], v[164:167], v[226:229], v[86:89]
	v_mfma_f32_16x16x32_bf16 v[114:117], v[152:155], v[240:243], v[114:117]
	v_mfma_f32_16x16x32_bf16 v[82:85], v[164:167], v[240:243], v[82:85]
	v_mfma_f32_16x16x32_bf16 v[126:129], v[160:163], v[214:217], v[126:129]
	v_mfma_f32_16x16x32_bf16 v[102:105], v[168:171], v[214:217], v[102:105]
	v_mfma_f32_16x16x32_bf16 v[122:125], v[160:163], v[222:225], v[122:125]
	v_mfma_f32_16x16x32_bf16 v[90:93], v[168:171], v[222:225], v[90:93]
	v_mfma_f32_16x16x32_bf16 v[118:121], v[160:163], v[230:233], v[118:121]
	v_mfma_f32_16x16x32_bf16 v[86:89], v[168:171], v[230:233], v[86:89]
	v_mfma_f32_16x16x32_bf16 v[114:117], v[160:163], v[244:247], v[114:117]
	v_mfma_f32_16x16x32_bf16 v[82:85], v[168:171], v[244:247], v[82:85]
	s_setprio 0
	s_setprio 1
	v_mfma_f32_16x16x32_bf16 v[62:65], v[172:175], v[194:197], v[62:65]
	v_mfma_f32_16x16x32_bf16 v[38:41], v[186:189], v[194:197], v[38:41]
	v_mfma_f32_16x16x32_bf16 v[58:61], v[172:175], v[218:221], v[58:61]
	v_mfma_f32_16x16x32_bf16 v[26:29], v[186:189], v[218:221], v[26:29]
	v_mfma_f32_16x16x32_bf16 v[54:57], v[172:175], v[226:229], v[54:57]
	v_mfma_f32_16x16x32_bf16 v[22:25], v[186:189], v[226:229], v[22:25]
	v_mfma_f32_16x16x32_bf16 v[50:53], v[172:175], v[240:243], v[50:53]
	v_mfma_f32_16x16x32_bf16 v[18:21], v[186:189], v[240:243], v[18:21]
	v_mfma_f32_16x16x32_bf16 v[62:65], v[176:179], v[214:217], v[62:65]
	v_mfma_f32_16x16x32_bf16 v[38:41], v[190:193], v[214:217], v[38:41]
	v_mfma_f32_16x16x32_bf16 v[58:61], v[176:179], v[222:225], v[58:61]
	v_mfma_f32_16x16x32_bf16 v[26:29], v[190:193], v[222:225], v[26:29]
	v_mfma_f32_16x16x32_bf16 v[54:57], v[176:179], v[230:233], v[54:57]
	v_mfma_f32_16x16x32_bf16 v[22:25], v[190:193], v[230:233], v[22:25]
	v_mfma_f32_16x16x32_bf16 v[50:53], v[176:179], v[244:247], v[50:53]
	v_mfma_f32_16x16x32_bf16 v[18:21], v[190:193], v[244:247], v[18:21]
	s_setprio 0
	s_barrier
	s_add_i32 s2, s18, s14
	v_lshl_add_u64 v[180:181], v[180:181], 0, s[54:55]
	s_mov_b32 m0, s2
	ds_read_b128 v[194:197], v158 offset:49152
	ds_read_b128 v[214:217], v158 offset:50176
	ds_read_b128 v[218:221], v158 offset:51200
	ds_read_b128 v[222:225], v158 offset:52224
	ds_read_b128 v[226:229], v158 offset:53248
	ds_read_b128 v[230:233], v158 offset:54272
	ds_read_b128 v[240:243], v158 offset:55296
	ds_read_b128 v[244:247], v158 offset:56320
	global_load_lds_dwordx4 v[180:181], off
	s_add_i32 m0, s2, 0x2000
	s_add_u32 s2, s22, 0x40080
	v_lshl_add_u64 v[180:181], v[234:235], 0, s[54:55]
	s_addc_u32 s3, s23, 0
	s_add_i32 s18, s19, s14
	global_load_lds_dwordx4 v[180:181], off
	s_waitcnt vmcnt(4)
	s_waitcnt lgkmcnt(0)
	s_barrier
	s_setprio 1
	s_waitcnt lgkmcnt(0)
	v_mfma_f32_16x16x32_bf16 v[110:113], v[152:155], v[194:197], v[110:113]
	v_mfma_f32_16x16x32_bf16 v[78:81], v[164:167], v[194:197], v[78:81]
	v_mfma_f32_16x16x32_bf16 v[106:109], v[152:155], v[218:221], v[106:109]
	v_mfma_f32_16x16x32_bf16 v[74:77], v[164:167], v[218:221], v[74:77]
	v_lshl_add_u64 v[180:181], s[2:3], 0, v[0:1]
	s_mov_b32 m0, s18
	s_nop 0
	global_load_lds_dwordx4 v[180:181], off
	v_mfma_f32_16x16x32_bf16 v[98:101], v[152:155], v[226:229], v[98:101]
	v_mfma_f32_16x16x32_bf16 v[70:73], v[164:167], v[226:229], v[70:73]
	v_mfma_f32_16x16x32_bf16 v[94:97], v[152:155], v[240:243], v[94:97]
	v_mfma_f32_16x16x32_bf16 v[66:69], v[164:167], v[240:243], v[66:69]
	v_mfma_f32_16x16x32_bf16 v[110:113], v[160:163], v[214:217], v[110:113]
	v_mfma_f32_16x16x32_bf16 v[78:81], v[168:171], v[214:217], v[78:81]
	v_mfma_f32_16x16x32_bf16 v[106:109], v[160:163], v[222:225], v[106:109]
	v_mfma_f32_16x16x32_bf16 v[74:77], v[168:171], v[222:225], v[74:77]
	v_lshl_add_u64 v[180:181], s[2:3], 0, v[130:131]
	s_add_i32 m0, s18, 0x2000
	s_nop 0
	global_load_lds_dwordx4 v[180:181], off
	v_mfma_f32_16x16x32_bf16 v[98:101], v[160:163], v[230:233], v[98:101]
	v_mfma_f32_16x16x32_bf16 v[70:73], v[168:171], v[230:233], v[70:73]
	v_mfma_f32_16x16x32_bf16 v[94:97], v[160:163], v[244:247], v[94:97]
	v_mfma_f32_16x16x32_bf16 v[66:69], v[168:171], v[244:247], v[66:69]
	s_setprio 0
	s_setprio 1
	v_mfma_f32_16x16x32_bf16 v[46:49], v[172:175], v[194:197], v[46:49]
	v_mfma_f32_16x16x32_bf16 v[14:17], v[186:189], v[194:197], v[14:17]
	v_mfma_f32_16x16x32_bf16 v[42:45], v[172:175], v[218:221], v[42:45]
	v_mfma_f32_16x16x32_bf16 v[10:13], v[186:189], v[218:221], v[10:13]
	v_lshl_add_u64 v[180:181], v[210:211], 0, s[54:55]
	s_mov_b32 m0, s30
	s_nop 0
	global_load_lds_dwordx4 v[180:181], off
	v_mfma_f32_16x16x32_bf16 v[34:37], v[172:175], v[226:229], v[34:37]
	v_mfma_f32_16x16x32_bf16 v[6:9], v[186:189], v[226:229], v[6:9]
	v_mfma_f32_16x16x32_bf16 v[30:33], v[172:175], v[240:243], v[30:33]
	v_mfma_f32_16x16x32_bf16 v[2:5], v[186:189], v[240:243], v[2:5]
	v_mfma_f32_16x16x32_bf16 v[46:49], v[176:179], v[214:217], v[46:49]
	v_mfma_f32_16x16x32_bf16 v[14:17], v[190:193], v[214:217], v[14:17]
	v_mfma_f32_16x16x32_bf16 v[42:45], v[176:179], v[222:225], v[42:45]
	v_mfma_f32_16x16x32_bf16 v[10:13], v[190:193], v[222:225], v[10:13]
	v_lshl_add_u64 v[180:181], v[182:183], 0, s[54:55]
	s_mov_b32 m0, s31
	s_nop 0
	global_load_lds_dwordx4 v[180:181], off
	v_mfma_f32_16x16x32_bf16 v[34:37], v[176:179], v[230:233], v[34:37]
	v_mfma_f32_16x16x32_bf16 v[6:9], v[190:193], v[230:233], v[6:9]
	v_mfma_f32_16x16x32_bf16 v[30:33], v[176:179], v[244:247], v[30:33]
	v_mfma_f32_16x16x32_bf16 v[2:5], v[190:193], v[244:247], v[2:5]
	s_setprio 0
	s_barrier
	s_add_i32 s37, s37, 2
	s_add_u32 s35, s35, 0x100
	s_addc_u32 s36, s36, 0
	s_cmp_gt_u32 s37, 13
	s_mov_b64 s[2:3], s[16:17]
	s_cbranch_scc0 .LBB0_1022
	s_and_b64 vcc, exec, s[42:43]
	s_cbranch_vccz .LBB0_1025
	s_barrier

.LBB0_1171:
	s_add_u32 s8, s6, 0xfffc0080
	s_addc_u32 s9, s7, -1
	s_add_i32 s18, 0, 0x10000
	s_cmp_eq_u32 s49, 12
	s_cselect_b32 s11, s0, s9
	s_cselect_b32 s10, s1, s8
	v_add_u32_e32 v144, s18, v147
	s_cselect_b32 s9, s12, s37
	s_cselect_b32 s8, s13, s36
	s_add_i32 s19, 0, 0x14000
	ds_read_b128 v[140:143], v144
	ds_read_b128 v[150:153], v144 offset:1024
	ds_read_b128 v[154:157], v144 offset:2048
	ds_read_b128 v[158:161], v144 offset:3072
	v_add_u32_e32 v144, s19, v147
	ds_read_b128 v[162:165], v144
	ds_read_b128 v[166:169], v144 offset:1024
	ds_read_b128 v[170:173], v144 offset:2048
	ds_read_b128 v[174:177], v144 offset:3072
	v_lshl_add_u64 v[144:145], s[6:7], 0, v[136:137]
	s_add_i32 m0, s3, 0xc000
	ds_read_b128 v[178:181], v149
	ds_read_b128 v[186:189], v149 offset:1024
	ds_read_b128 v[190:193], v149 offset:2048
	ds_read_b128 v[194:197], v149 offset:3072
	ds_read_b128 v[214:217], v149 offset:4096
	ds_read_b128 v[218:221], v149 offset:5120
	ds_read_b128 v[222:225], v149 offset:6144
	ds_read_b128 v[226:229], v149 offset:7168
	global_load_lds_dwordx4 v[144:145], off
	v_lshl_add_u64 v[144:145], s[6:7], 0, v[138:139]
	s_add_i32 m0, s3, 0xe000
	s_nop 0
	global_load_lds_dwordx4 v[144:145], off
	s_waitcnt vmcnt(8)
	s_waitcnt lgkmcnt(0)
	s_barrier
	s_setprio 1
	s_waitcnt lgkmcnt(0)
	v_mfma_f32_16x16x32_bf16 v[126:129], v[140:143], v[178:181], v[126:129]
	v_mfma_f32_16x16x32_bf16 v[118:121], v[154:157], v[178:181], v[118:121]
	v_mfma_f32_16x16x32_bf16 v[110:113], v[140:143], v[190:193], v[110:113]
	v_mfma_f32_16x16x32_bf16 v[102:105], v[154:157], v[190:193], v[102:105]
	v_mfma_f32_16x16x32_bf16 v[94:97], v[140:143], v[214:217], v[94:97]
	v_mfma_f32_16x16x32_bf16 v[86:89], v[154:157], v[214:217], v[86:89]
	v_mfma_f32_16x16x32_bf16 v[78:81], v[140:143], v[222:225], v[78:81]
	v_mfma_f32_16x16x32_bf16 v[70:73], v[154:157], v[222:225], v[70:73]
	v_mfma_f32_16x16x32_bf16 v[126:129], v[150:153], v[186:189], v[126:129]
	v_mfma_f32_16x16x32_bf16 v[118:121], v[158:161], v[186:189], v[118:121]
	v_mfma_f32_16x16x32_bf16 v[110:113], v[150:153], v[194:197], v[110:113]
	v_mfma_f32_16x16x32_bf16 v[102:105], v[158:161], v[194:197], v[102:105]
	v_mfma_f32_16x16x32_bf16 v[94:97], v[150:153], v[218:221], v[94:97]
	v_mfma_f32_16x16x32_bf16 v[86:89], v[158:161], v[218:221], v[86:89]
	v_mfma_f32_16x16x32_bf16 v[78:81], v[150:153], v[226:229], v[78:81]
	v_mfma_f32_16x16x32_bf16 v[70:73], v[158:161], v[226:229], v[70:73]
	s_setprio 0
	s_setprio 1
	v_mfma_f32_16x16x32_bf16 v[122:125], v[162:165], v[178:181], v[122:125]
	v_mfma_f32_16x16x32_bf16 v[114:117], v[170:173], v[178:181], v[114:117]
	v_mfma_f32_16x16x32_bf16 v[106:109], v[162:165], v[190:193], v[106:109]
	v_mfma_f32_16x16x32_bf16 v[98:101], v[170:173], v[190:193], v[98:101]
	v_mfma_f32_16x16x32_bf16 v[90:93], v[162:165], v[214:217], v[90:93]
	v_mfma_f32_16x16x32_bf16 v[82:85], v[170:173], v[214:217], v[82:85]
	v_mfma_f32_16x16x32_bf16 v[74:77], v[162:165], v[222:225], v[74:77]
	v_mfma_f32_16x16x32_bf16 v[66:69], v[170:173], v[222:225], v[66:69]
	v_mfma_f32_16x16x32_bf16 v[122:125], v[166:169], v[186:189], v[122:125]
	v_mfma_f32_16x16x32_bf16 v[114:117], v[174:177], v[186:189], v[114:117]
	v_mfma_f32_16x16x32_bf16 v[106:109], v[166:169], v[194:197], v[106:109]
	v_mfma_f32_16x16x32_bf16 v[98:101], v[174:177], v[194:197], v[98:101]
	v_mfma_f32_16x16x32_bf16 v[90:93], v[166:169], v[218:221], v[90:93]
	v_mfma_f32_16x16x32_bf16 v[82:85], v[174:177], v[218:221], v[82:85]
	v_mfma_f32_16x16x32_bf16 v[74:77], v[166:169], v[226:229], v[74:77]
	v_mfma_f32_16x16x32_bf16 v[66:69], v[174:177], v[226:229], v[66:69]
	s_setprio 0
	s_barrier
	s_add_i32 s18, s18, s28
	v_lshl_add_u64 v[144:145], s[8:9], 0, v[0:1]
	s_mov_b32 m0, s18
	ds_read_b128 v[178:181], v149 offset:16384
	ds_read_b128 v[186:189], v149 offset:17408
	ds_read_b128 v[190:193], v149 offset:18432
	ds_read_b128 v[194:197], v149 offset:19456
	ds_read_b128 v[214:217], v149 offset:20480
	ds_read_b128 v[218:221], v149 offset:21504
	ds_read_b128 v[222:225], v149 offset:22528
	ds_read_b128 v[226:229], v149 offset:23552
	global_load_lds_dwordx4 v[144:145], off
	s_add_i32 m0, s18, 0x2000
	s_add_u32 s56, s8, 0x40000
	v_lshl_add_u64 v[182:183], s[8:9], 0, v[130:131]
	s_addc_u32 s57, s9, 0
	s_add_i32 s18, s19, s28
	global_load_lds_dwordx4 v[182:183], off
	s_waitcnt vmcnt(4)
	s_waitcnt lgkmcnt(0)
	s_barrier
	s_setprio 1
	s_waitcnt lgkmcnt(0)
	v_mfma_f32_16x16x32_bf16 v[62:65], v[140:143], v[178:181], v[62:65]
	v_mfma_f32_16x16x32_bf16 v[54:57], v[154:157], v[178:181], v[54:57]
	v_mfma_f32_16x16x32_bf16 v[46:49], v[140:143], v[190:193], v[46:49]
	v_mfma_f32_16x16x32_bf16 v[38:41], v[154:157], v[190:193], v[38:41]
	v_lshl_add_u64 v[184:185], s[56:57], 0, v[0:1]
	s_mov_b32 m0, s18
	v_lshl_add_u64 v[210:211], s[10:11], 0, v[132:133]
	global_load_lds_dwordx4 v[184:185], off
	v_mfma_f32_16x16x32_bf16 v[30:33], v[140:143], v[214:217], v[30:33]
	v_mfma_f32_16x16x32_bf16 v[22:25], v[154:157], v[214:217], v[22:25]
	v_mfma_f32_16x16x32_bf16 v[14:17], v[140:143], v[222:225], v[14:17]
	v_mfma_f32_16x16x32_bf16 v[6:9], v[154:157], v[222:225], v[6:9]
	v_mfma_f32_16x16x32_bf16 v[62:65], v[150:153], v[186:189], v[62:65]
	v_mfma_f32_16x16x32_bf16 v[54:57], v[158:161], v[186:189], v[54:57]
	v_mfma_f32_16x16x32_bf16 v[46:49], v[150:153], v[194:197], v[46:49]
	v_mfma_f32_16x16x32_bf16 v[38:41], v[158:161], v[194:197], v[38:41]
	v_lshl_add_u64 v[184:185], s[56:57], 0, v[130:131]
	s_add_i32 m0, s18, 0x2000
	s_nop 0
	global_load_lds_dwordx4 v[184:185], off
	v_mfma_f32_16x16x32_bf16 v[30:33], v[150:153], v[218:221], v[30:33]
	v_mfma_f32_16x16x32_bf16 v[22:25], v[158:161], v[218:221], v[22:25]
	v_mfma_f32_16x16x32_bf16 v[14:17], v[150:153], v[226:229], v[14:17]
	v_mfma_f32_16x16x32_bf16 v[6:9], v[158:161], v[226:229], v[6:9]
	s_setprio 0
	s_setprio 1
	v_mfma_f32_16x16x32_bf16 v[58:61], v[162:165], v[178:181], v[58:61]
	v_mfma_f32_16x16x32_bf16 v[50:53], v[170:173], v[178:181], v[50:53]
	v_mfma_f32_16x16x32_bf16 v[42:45], v[162:165], v[190:193], v[42:45]
	v_mfma_f32_16x16x32_bf16 v[34:37], v[170:173], v[190:193], v[34:37]
	v_lshl_add_u64 v[184:185], s[10:11], 0, v[134:135]
	s_mov_b32 m0, s3
	s_nop 0
	global_load_lds_dwordx4 v[184:185], off
	v_mfma_f32_16x16x32_bf16 v[26:29], v[162:165], v[214:217], v[26:29]
	v_mfma_f32_16x16x32_bf16 v[18:21], v[170:173], v[214:217], v[18:21]
	v_mfma_f32_16x16x32_bf16 v[10:13], v[162:165], v[222:225], v[10:13]
	v_mfma_f32_16x16x32_bf16 v[2:5], v[170:173], v[222:225], v[2:5]
	v_mfma_f32_16x16x32_bf16 v[58:61], v[166:169], v[186:189], v[58:61]
	v_mfma_f32_16x16x32_bf16 v[50:53], v[174:177], v[186:189], v[50:53]
	v_mfma_f32_16x16x32_bf16 v[42:45], v[166:169], v[194:197], v[42:45]
	v_mfma_f32_16x16x32_bf16 v[34:37], v[174:177], v[194:197], v[34:37]
	s_mov_b32 m0, s5
	s_nop 0
	global_load_lds_dwordx4 v[210:211], off
	v_mfma_f32_16x16x32_bf16 v[26:29], v[166:169], v[218:221], v[26:29]
	v_mfma_f32_16x16x32_bf16 v[18:21], v[174:177], v[218:221], v[18:21]
	v_mfma_f32_16x16x32_bf16 v[10:13], v[166:169], v[226:229], v[10:13]
	v_mfma_f32_16x16x32_bf16 v[2:5], v[174:177], v[226:229], v[2:5]
	s_setprio 0
	s_barrier
	s_add_i32 s18, 0, 0x18000
	s_add_i32 s19, 0, 0x1c000
	v_add_u32_e32 v158, s18, v147
	v_add_u32_e32 v174, s19, v147
	ds_read_b128 v[140:143], v158
	ds_read_b128 v[150:153], v158 offset:1024
	ds_read_b128 v[154:157], v158 offset:2048
	ds_read_b128 v[158:161], v158 offset:3072
	ds_read_b128 v[162:165], v174
	ds_read_b128 v[166:169], v174 offset:1024
	ds_read_b128 v[170:173], v174 offset:2048
	ds_read_b128 v[174:177], v174 offset:3072
	s_add_u32 s10, s10, 0x40000
	s_addc_u32 s11, s11, 0
	s_mov_b32 m0, s29
	v_lshl_add_u64 v[230:231], s[10:11], 0, v[134:135]
	ds_read_b128 v[178:181], v149 offset:32768
	ds_read_b128 v[186:189], v149 offset:33792
	ds_read_b128 v[190:193], v149 offset:34816
	ds_read_b128 v[194:197], v149 offset:35840
	ds_read_b128 v[214:217], v149 offset:36864
	ds_read_b128 v[218:221], v149 offset:37888
	ds_read_b128 v[222:225], v149 offset:38912
	ds_read_b128 v[226:229], v149 offset:39936
	global_load_lds_dwordx4 v[230:231], off
	v_lshl_add_u64 v[230:231], s[10:11], 0, v[132:133]
	s_mov_b32 m0, s30
	s_nop 0
	global_load_lds_dwordx4 v[230:231], off
	s_waitcnt vmcnt(8)
	s_waitcnt lgkmcnt(0)
	s_barrier
	s_setprio 1
	s_waitcnt lgkmcnt(0)
	v_mfma_f32_16x16x32_bf16 v[126:129], v[140:143], v[178:181], v[126:129]
	v_mfma_f32_16x16x32_bf16 v[118:121], v[154:157], v[178:181], v[118:121]
	v_mfma_f32_16x16x32_bf16 v[110:113], v[140:143], v[190:193], v[110:113]
	v_mfma_f32_16x16x32_bf16 v[102:105], v[154:157], v[190:193], v[102:105]
	v_mfma_f32_16x16x32_bf16 v[94:97], v[140:143], v[214:217], v[94:97]
	v_mfma_f32_16x16x32_bf16 v[86:89], v[154:157], v[214:217], v[86:89]
	v_mfma_f32_16x16x32_bf16 v[78:81], v[140:143], v[222:225], v[78:81]
	v_mfma_f32_16x16x32_bf16 v[70:73], v[154:157], v[222:225], v[70:73]
	v_mfma_f32_16x16x32_bf16 v[126:129], v[150:153], v[186:189], v[126:129]
	v_mfma_f32_16x16x32_bf16 v[118:121], v[158:161], v[186:189], v[118:121]
	v_mfma_f32_16x16x32_bf16 v[110:113], v[150:153], v[194:197], v[110:113]
	v_mfma_f32_16x16x32_bf16 v[102:105], v[158:161], v[194:197], v[102:105]
	v_mfma_f32_16x16x32_bf16 v[94:97], v[150:153], v[218:221], v[94:97]
	v_mfma_f32_16x16x32_bf16 v[86:89], v[158:161], v[218:221], v[86:89]
	v_mfma_f32_16x16x32_bf16 v[78:81], v[150:153], v[226:229], v[78:81]
	v_mfma_f32_16x16x32_bf16 v[70:73], v[158:161], v[226:229], v[70:73]
	s_setprio 0
	s_setprio 1
	v_mfma_f32_16x16x32_bf16 v[122:125], v[162:165], v[178:181], v[122:125]
	v_mfma_f32_16x16x32_bf16 v[114:117], v[170:173], v[178:181], v[114:117]
	v_mfma_f32_16x16x32_bf16 v[106:109], v[162:165], v[190:193], v[106:109]
	v_mfma_f32_16x16x32_bf16 v[98:101], v[170:173], v[190:193], v[98:101]
	v_mfma_f32_16x16x32_bf16 v[90:93], v[162:165], v[214:217], v[90:93]
	v_mfma_f32_16x16x32_bf16 v[82:85], v[170:173], v[214:217], v[82:85]
	v_mfma_f32_16x16x32_bf16 v[74:77], v[162:165], v[222:225], v[74:77]
	v_mfma_f32_16x16x32_bf16 v[66:69], v[170:173], v[222:225], v[66:69]
	v_mfma_f32_16x16x32_bf16 v[122:125], v[166:169], v[186:189], v[122:125]
	v_mfma_f32_16x16x32_bf16 v[114:117], v[174:177], v[186:189], v[114:117]
	v_mfma_f32_16x16x32_bf16 v[106:109], v[166:169], v[194:197], v[106:109]
	v_mfma_f32_16x16x32_bf16 v[98:101], v[174:177], v[194:197], v[98:101]
	v_mfma_f32_16x16x32_bf16 v[90:93], v[166:169], v[218:221], v[90:93]
	v_mfma_f32_16x16x32_bf16 v[82:85], v[174:177], v[218:221], v[82:85]
	v_mfma_f32_16x16x32_bf16 v[74:77], v[166:169], v[226:229], v[74:77]
	v_mfma_f32_16x16x32_bf16 v[66:69], v[174:177], v[226:229], v[66:69]
	s_setprio 0
	s_barrier
	s_add_i32 s10, s18, s28
	v_lshl_add_u64 v[144:145], v[144:145], 0, s[54:55]
	s_mov_b32 m0, s10
	ds_read_b128 v[178:181], v149 offset:49152
	ds_read_b128 v[186:189], v149 offset:50176
	ds_read_b128 v[190:193], v149 offset:51200
	ds_read_b128 v[194:197], v149 offset:52224
	ds_read_b128 v[214:217], v149 offset:53248
	ds_read_b128 v[218:221], v149 offset:54272
	ds_read_b128 v[222:225], v149 offset:55296
	ds_read_b128 v[226:229], v149 offset:56320
	global_load_lds_dwordx4 v[144:145], off
	s_add_i32 m0, s10, 0x2000
	s_add_u32 s8, s8, 0x40080
	v_lshl_add_u64 v[144:145], v[182:183], 0, s[54:55]
	s_addc_u32 s9, s9, 0
	s_add_i32 s10, s19, s28
	global_load_lds_dwordx4 v[144:145], off
	s_waitcnt vmcnt(4)
	s_waitcnt lgkmcnt(0)
	s_barrier
	s_setprio 1
	s_waitcnt lgkmcnt(0)
	v_mfma_f32_16x16x32_bf16 v[62:65], v[140:143], v[178:181], v[62:65]
	v_mfma_f32_16x16x32_bf16 v[54:57], v[154:157], v[178:181], v[54:57]
	v_mfma_f32_16x16x32_bf16 v[46:49], v[140:143], v[190:193], v[46:49]
	v_mfma_f32_16x16x32_bf16 v[38:41], v[154:157], v[190:193], v[38:41]
	v_lshl_add_u64 v[144:145], s[8:9], 0, v[0:1]
	s_mov_b32 m0, s10
	s_nop 0
	global_load_lds_dwordx4 v[144:145], off
	v_mfma_f32_16x16x32_bf16 v[30:33], v[140:143], v[214:217], v[30:33]
	v_mfma_f32_16x16x32_bf16 v[22:25], v[154:157], v[214:217], v[22:25]
	v_mfma_f32_16x16x32_bf16 v[14:17], v[140:143], v[222:225], v[14:17]
	v_mfma_f32_16x16x32_bf16 v[6:9], v[154:157], v[222:225], v[6:9]
	v_mfma_f32_16x16x32_bf16 v[62:65], v[150:153], v[186:189], v[62:65]
	v_mfma_f32_16x16x32_bf16 v[54:57], v[158:161], v[186:189], v[54:57]
	v_mfma_f32_16x16x32_bf16 v[46:49], v[150:153], v[194:197], v[46:49]
	v_mfma_f32_16x16x32_bf16 v[38:41], v[158:161], v[194:197], v[38:41]
	v_lshl_add_u64 v[144:145], s[8:9], 0, v[130:131]
	s_add_i32 m0, s10, 0x2000
	s_nop 0
	global_load_lds_dwordx4 v[144:145], off
	v_mfma_f32_16x16x32_bf16 v[30:33], v[150:153], v[218:221], v[30:33]
	v_mfma_f32_16x16x32_bf16 v[22:25], v[158:161], v[218:221], v[22:25]
	v_mfma_f32_16x16x32_bf16 v[14:17], v[150:153], v[226:229], v[14:17]
	v_mfma_f32_16x16x32_bf16 v[6:9], v[158:161], v[226:229], v[6:9]
	s_setprio 0
	s_setprio 1
	v_mfma_f32_16x16x32_bf16 v[58:61], v[162:165], v[178:181], v[58:61]
	v_mfma_f32_16x16x32_bf16 v[50:53], v[170:173], v[178:181], v[50:53]
	v_mfma_f32_16x16x32_bf16 v[42:45], v[162:165], v[190:193], v[42:45]
	v_mfma_f32_16x16x32_bf16 v[34:37], v[170:173], v[190:193], v[34:37]
	v_lshl_add_u64 v[144:145], v[184:185], 0, s[54:55]
	s_mov_b32 m0, s31
	s_nop 0
	global_load_lds_dwordx4 v[144:145], off
	v_mfma_f32_16x16x32_bf16 v[26:29], v[162:165], v[214:217], v[26:29]
	v_mfma_f32_16x16x32_bf16 v[18:21], v[170:173], v[214:217], v[18:21]
	v_mfma_f32_16x16x32_bf16 v[10:13], v[162:165], v[222:225], v[10:13]
	v_mfma_f32_16x16x32_bf16 v[2:5], v[170:173], v[222:225], v[2:5]
	v_mfma_f32_16x16x32_bf16 v[58:61], v[166:169], v[186:189], v[58:61]
	v_mfma_f32_16x16x32_bf16 v[50:53], v[174:177], v[186:189], v[50:53]
	v_mfma_f32_16x16x32_bf16 v[42:45], v[166:169], v[194:197], v[42:45]
	v_mfma_f32_16x16x32_bf16 v[34:37], v[174:177], v[194:197], v[34:37]
	v_lshl_add_u64 v[144:145], v[210:211], 0, s[54:55]
	s_mov_b32 m0, s34
	s_nop 0
	global_load_lds_dwordx4 v[144:145], off
	v_mfma_f32_16x16x32_bf16 v[26:29], v[166:169], v[218:221], v[26:29]
	v_mfma_f32_16x16x32_bf16 v[18:21], v[174:177], v[218:221], v[18:21]
	v_mfma_f32_16x16x32_bf16 v[10:13], v[166:169], v[226:229], v[10:13]
	v_mfma_f32_16x16x32_bf16 v[2:5], v[174:177], v[226:229], v[2:5]
	s_setprio 0
	s_barrier
	s_add_i32 s49, s49, 2
	s_add_u32 s6, s6, 0x100
	s_addc_u32 s7, s7, 0
	s_add_u32 s36, s36, 0x100
	s_addc_u32 s37, s37, 0
	s_cmp_gt_u32 s49, 13
	s_cbranch_scc0 .LBB0_1171
	s_and_b64 vcc, exec, s[46:47]
	s_cbranch_vccz .LBB0_1174
	s_barrier

.LBB0_1247:
	s_add_u32 s8, s2, 0x100
	s_addc_u32 s9, s3, 0
	s_add_i32 s18, 0, 0x10000
	s_cmp_eq_u32 s40, 40
	s_cselect_b32 s17, s5, s9
	s_cselect_b32 s16, s4, s8
	v_add_u32_e32 v159, s18, v156
	s_cselect_b32 s11, s7, s1
	s_cselect_b32 s10, s6, s0
	s_add_i32 s19, 0, 0x14000
	ds_read_b128 v[152:155], v159
	ds_read_b128 v[160:163], v159 offset:1024
	ds_read_b128 v[164:167], v159 offset:2048
	ds_read_b128 v[168:171], v159 offset:3072
	v_add_u32_e32 v159, s19, v156
	ds_read_b128 v[172:175], v159
	ds_read_b128 v[176:179], v159 offset:1024
	ds_read_b128 v[186:189], v159 offset:2048
	ds_read_b128 v[190:193], v159 offset:3072
	v_lshl_add_u64 v[180:181], s[2:3], 0, v[148:149]
	s_add_i32 m0, s23, 0xc000
	ds_read_b128 v[194:197], v158
	ds_read_b128 v[214:217], v158 offset:1024
	ds_read_b128 v[218:221], v158 offset:2048
	ds_read_b128 v[222:225], v158 offset:3072
	ds_read_b128 v[226:229], v158 offset:4096
	ds_read_b128 v[230:233], v158 offset:5120
	ds_read_b128 v[240:243], v158 offset:6144
	ds_read_b128 v[244:247], v158 offset:7168
	global_load_lds_dwordx4 v[180:181], off
	v_lshl_add_u64 v[180:181], s[2:3], 0, v[150:151]
	s_add_i32 m0, s23, 0xe000
	s_nop 0
	global_load_lds_dwordx4 v[180:181], off
	s_waitcnt vmcnt(8)
	s_waitcnt lgkmcnt(0)
	s_barrier
	s_setprio 1
	s_waitcnt lgkmcnt(0)
	v_mfma_f32_16x16x32_bf16 v[126:129], v[152:155], v[194:197], v[126:129]
	v_mfma_f32_16x16x32_bf16 v[98:101], v[164:167], v[194:197], v[98:101]
	v_mfma_f32_16x16x32_bf16 v[122:125], v[152:155], v[218:221], v[122:125]
	v_mfma_f32_16x16x32_bf16 v[90:93], v[164:167], v[218:221], v[90:93]
	v_mfma_f32_16x16x32_bf16 v[118:121], v[152:155], v[226:229], v[118:121]
	v_mfma_f32_16x16x32_bf16 v[86:89], v[164:167], v[226:229], v[86:89]
	v_mfma_f32_16x16x32_bf16 v[114:117], v[152:155], v[240:243], v[114:117]
	v_mfma_f32_16x16x32_bf16 v[82:85], v[164:167], v[240:243], v[82:85]
	v_mfma_f32_16x16x32_bf16 v[126:129], v[160:163], v[214:217], v[126:129]
	v_mfma_f32_16x16x32_bf16 v[98:101], v[168:171], v[214:217], v[98:101]
	v_mfma_f32_16x16x32_bf16 v[122:125], v[160:163], v[222:225], v[122:125]
	v_mfma_f32_16x16x32_bf16 v[90:93], v[168:171], v[222:225], v[90:93]
	v_mfma_f32_16x16x32_bf16 v[118:121], v[160:163], v[230:233], v[118:121]
	v_mfma_f32_16x16x32_bf16 v[86:89], v[168:171], v[230:233], v[86:89]
	v_mfma_f32_16x16x32_bf16 v[114:117], v[160:163], v[244:247], v[114:117]
	v_mfma_f32_16x16x32_bf16 v[82:85], v[168:171], v[244:247], v[82:85]
	s_setprio 0
	s_setprio 1
	v_mfma_f32_16x16x32_bf16 v[66:69], v[172:175], v[194:197], v[66:69]
	v_mfma_f32_16x16x32_bf16 v[34:37], v[186:189], v[194:197], v[34:37]
	v_mfma_f32_16x16x32_bf16 v[58:61], v[172:175], v[218:221], v[58:61]
	v_mfma_f32_16x16x32_bf16 v[26:29], v[186:189], v[218:221], v[26:29]
	v_mfma_f32_16x16x32_bf16 v[54:57], v[172:175], v[226:229], v[54:57]
	v_mfma_f32_16x16x32_bf16 v[22:25], v[186:189], v[226:229], v[22:25]
	v_mfma_f32_16x16x32_bf16 v[50:53], v[172:175], v[240:243], v[50:53]
	v_mfma_f32_16x16x32_bf16 v[18:21], v[186:189], v[240:243], v[18:21]
	v_mfma_f32_16x16x32_bf16 v[66:69], v[176:179], v[214:217], v[66:69]
	v_mfma_f32_16x16x32_bf16 v[34:37], v[190:193], v[214:217], v[34:37]
	v_mfma_f32_16x16x32_bf16 v[58:61], v[176:179], v[222:225], v[58:61]
	v_mfma_f32_16x16x32_bf16 v[26:29], v[190:193], v[222:225], v[26:29]
	v_mfma_f32_16x16x32_bf16 v[54:57], v[176:179], v[230:233], v[54:57]
	v_mfma_f32_16x16x32_bf16 v[22:25], v[190:193], v[230:233], v[22:25]
	v_mfma_f32_16x16x32_bf16 v[50:53], v[176:179], v[244:247], v[50:53]
	v_mfma_f32_16x16x32_bf16 v[18:21], v[190:193], v[244:247], v[18:21]
	s_setprio 0
	s_barrier
	s_add_i32 s2, s18, s22
	v_lshl_add_u64 v[180:181], s[10:11], 0, v[0:1]
	s_mov_b32 m0, s2
	ds_read_b128 v[194:197], v158 offset:16384
	ds_read_b128 v[214:217], v158 offset:17408
	ds_read_b128 v[218:221], v158 offset:18432
	ds_read_b128 v[222:225], v158 offset:19456
	ds_read_b128 v[226:229], v158 offset:20480
	ds_read_b128 v[230:233], v158 offset:21504
	ds_read_b128 v[240:243], v158 offset:22528
	ds_read_b128 v[244:247], v158 offset:23552
	global_load_lds_dwordx4 v[180:181], off
	s_add_i32 m0, s2, 0x2000
	s_add_u32 s2, s10, 0xb0000
	v_lshl_add_u64 v[182:183], s[10:11], 0, v[130:131]
	s_addc_u32 s3, s11, 0
	s_add_i32 s18, s19, s22
	global_load_lds_dwordx4 v[182:183], off
	s_waitcnt vmcnt(4)
	s_waitcnt lgkmcnt(0)
	s_barrier
	s_setprio 1
	s_waitcnt lgkmcnt(0)
	v_mfma_f32_16x16x32_bf16 v[110:113], v[152:155], v[194:197], v[110:113]
	v_mfma_f32_16x16x32_bf16 v[78:81], v[164:167], v[194:197], v[78:81]
	v_mfma_f32_16x16x32_bf16 v[106:109], v[152:155], v[218:221], v[106:109]
	v_mfma_f32_16x16x32_bf16 v[74:77], v[164:167], v[218:221], v[74:77]
	v_lshl_add_u64 v[184:185], s[2:3], 0, v[0:1]
	s_mov_b32 m0, s18
	v_lshl_add_u64 v[210:211], s[16:17], 0, v[130:131]
	global_load_lds_dwordx4 v[184:185], off
	v_mfma_f32_16x16x32_bf16 v[102:105], v[152:155], v[226:229], v[102:105]
	v_mfma_f32_16x16x32_bf16 v[70:73], v[164:167], v[226:229], v[70:73]
	v_mfma_f32_16x16x32_bf16 v[94:97], v[152:155], v[240:243], v[94:97]
	v_mfma_f32_16x16x32_bf16 v[62:65], v[164:167], v[240:243], v[62:65]
	v_mfma_f32_16x16x32_bf16 v[110:113], v[160:163], v[214:217], v[110:113]
	v_mfma_f32_16x16x32_bf16 v[78:81], v[168:171], v[214:217], v[78:81]
	v_mfma_f32_16x16x32_bf16 v[106:109], v[160:163], v[222:225], v[106:109]
	v_mfma_f32_16x16x32_bf16 v[74:77], v[168:171], v[222:225], v[74:77]
	v_lshl_add_u64 v[184:185], s[2:3], 0, v[130:131]
	s_add_i32 m0, s18, 0x2000
	s_nop 0
	global_load_lds_dwordx4 v[184:185], off
	v_mfma_f32_16x16x32_bf16 v[102:105], v[160:163], v[230:233], v[102:105]
	v_mfma_f32_16x16x32_bf16 v[70:73], v[168:171], v[230:233], v[70:73]
	v_mfma_f32_16x16x32_bf16 v[94:97], v[160:163], v[244:247], v[94:97]
	v_mfma_f32_16x16x32_bf16 v[62:65], v[168:171], v[244:247], v[62:65]
	s_setprio 0
	s_setprio 1
	v_mfma_f32_16x16x32_bf16 v[46:49], v[172:175], v[194:197], v[46:49]
	v_mfma_f32_16x16x32_bf16 v[14:17], v[186:189], v[194:197], v[14:17]
	v_mfma_f32_16x16x32_bf16 v[42:45], v[172:175], v[218:221], v[42:45]
	v_mfma_f32_16x16x32_bf16 v[10:13], v[186:189], v[218:221], v[10:13]
	v_lshl_add_u64 v[184:185], s[16:17], 0, v[0:1]
	s_mov_b32 m0, s23
	s_nop 0
	global_load_lds_dwordx4 v[184:185], off
	v_mfma_f32_16x16x32_bf16 v[38:41], v[172:175], v[226:229], v[38:41]
	v_mfma_f32_16x16x32_bf16 v[6:9], v[186:189], v[226:229], v[6:9]
	v_mfma_f32_16x16x32_bf16 v[30:33], v[172:175], v[240:243], v[30:33]
	v_mfma_f32_16x16x32_bf16 v[2:5], v[186:189], v[240:243], v[2:5]
	v_mfma_f32_16x16x32_bf16 v[46:49], v[176:179], v[214:217], v[46:49]
	v_mfma_f32_16x16x32_bf16 v[14:17], v[190:193], v[214:217], v[14:17]
	v_mfma_f32_16x16x32_bf16 v[42:45], v[176:179], v[222:225], v[42:45]
	v_mfma_f32_16x16x32_bf16 v[10:13], v[190:193], v[222:225], v[10:13]
	s_mov_b32 m0, s24
	s_nop 0
	global_load_lds_dwordx4 v[210:211], off
	v_mfma_f32_16x16x32_bf16 v[38:41], v[176:179], v[230:233], v[38:41]
	v_mfma_f32_16x16x32_bf16 v[6:9], v[190:193], v[230:233], v[6:9]
	v_mfma_f32_16x16x32_bf16 v[30:33], v[176:179], v[244:247], v[30:33]
	v_mfma_f32_16x16x32_bf16 v[2:5], v[190:193], v[244:247], v[2:5]
	s_setprio 0
	s_barrier
	s_add_i32 s18, 0, 0x18000
	v_add_u32_e32 v159, s18, v156
	s_add_i32 s19, 0, 0x1c000
	ds_read_b128 v[152:155], v159
	ds_read_b128 v[160:163], v159 offset:1024
	ds_read_b128 v[164:167], v159 offset:2048
	ds_read_b128 v[168:171], v159 offset:3072
	v_add_u32_e32 v159, s19, v156
	ds_read_b128 v[172:175], v159
	ds_read_b128 v[176:179], v159 offset:1024
	ds_read_b128 v[186:189], v159 offset:2048
	ds_read_b128 v[190:193], v159 offset:3072
	s_add_u32 s2, s16, 0xb0000
	s_addc_u32 s3, s17, 0
	s_mov_b32 m0, s25
	v_lshl_add_u64 v[234:235], s[2:3], 0, v[0:1]
	ds_read_b128 v[194:197], v158 offset:32768
	ds_read_b128 v[214:217], v158 offset:33792
	ds_read_b128 v[218:221], v158 offset:34816
	ds_read_b128 v[222:225], v158 offset:35840
	ds_read_b128 v[226:229], v158 offset:36864
	ds_read_b128 v[230:233], v158 offset:37888
	ds_read_b128 v[240:243], v158 offset:38912
	ds_read_b128 v[244:247], v158 offset:39936
	global_load_lds_dwordx4 v[234:235], off
	v_lshl_add_u64 v[234:235], s[2:3], 0, v[130:131]
	s_mov_b32 m0, s28
	s_nop 0
	global_load_lds_dwordx4 v[234:235], off
	s_waitcnt vmcnt(8)
	s_waitcnt lgkmcnt(0)
	s_barrier
	s_setprio 1
	s_waitcnt lgkmcnt(0)
	v_mfma_f32_16x16x32_bf16 v[126:129], v[152:155], v[194:197], v[126:129]
	v_mfma_f32_16x16x32_bf16 v[98:101], v[164:167], v[194:197], v[98:101]
	v_mfma_f32_16x16x32_bf16 v[122:125], v[152:155], v[218:221], v[122:125]
	v_mfma_f32_16x16x32_bf16 v[90:93], v[164:167], v[218:221], v[90:93]
	v_mfma_f32_16x16x32_bf16 v[118:121], v[152:155], v[226:229], v[118:121]
	v_mfma_f32_16x16x32_bf16 v[86:89], v[164:167], v[226:229], v[86:89]
	v_mfma_f32_16x16x32_bf16 v[114:117], v[152:155], v[240:243], v[114:117]
	v_mfma_f32_16x16x32_bf16 v[82:85], v[164:167], v[240:243], v[82:85]
	v_mfma_f32_16x16x32_bf16 v[126:129], v[160:163], v[214:217], v[126:129]
	v_mfma_f32_16x16x32_bf16 v[98:101], v[168:171], v[214:217], v[98:101]
	v_mfma_f32_16x16x32_bf16 v[122:125], v[160:163], v[222:225], v[122:125]
	v_mfma_f32_16x16x32_bf16 v[90:93], v[168:171], v[222:225], v[90:93]
	v_mfma_f32_16x16x32_bf16 v[118:121], v[160:163], v[230:233], v[118:121]
	v_mfma_f32_16x16x32_bf16 v[86:89], v[168:171], v[230:233], v[86:89]
	v_mfma_f32_16x16x32_bf16 v[114:117], v[160:163], v[244:247], v[114:117]
	v_mfma_f32_16x16x32_bf16 v[82:85], v[168:171], v[244:247], v[82:85]
	s_setprio 0
	s_setprio 1
	v_mfma_f32_16x16x32_bf16 v[66:69], v[172:175], v[194:197], v[66:69]
	v_mfma_f32_16x16x32_bf16 v[34:37], v[186:189], v[194:197], v[34:37]
	v_mfma_f32_16x16x32_bf16 v[58:61], v[172:175], v[218:221], v[58:61]
	v_mfma_f32_16x16x32_bf16 v[26:29], v[186:189], v[218:221], v[26:29]
	v_mfma_f32_16x16x32_bf16 v[54:57], v[172:175], v[226:229], v[54:57]
	v_mfma_f32_16x16x32_bf16 v[22:25], v[186:189], v[226:229], v[22:25]
	v_mfma_f32_16x16x32_bf16 v[50:53], v[172:175], v[240:243], v[50:53]
	v_mfma_f32_16x16x32_bf16 v[18:21], v[186:189], v[240:243], v[18:21]
	v_mfma_f32_16x16x32_bf16 v[66:69], v[176:179], v[214:217], v[66:69]
	v_mfma_f32_16x16x32_bf16 v[34:37], v[190:193], v[214:217], v[34:37]
	v_mfma_f32_16x16x32_bf16 v[58:61], v[176:179], v[222:225], v[58:61]
	v_mfma_f32_16x16x32_bf16 v[26:29], v[190:193], v[222:225], v[26:29]
	v_mfma_f32_16x16x32_bf16 v[54:57], v[176:179], v[230:233], v[54:57]
	v_mfma_f32_16x16x32_bf16 v[22:25], v[190:193], v[230:233], v[22:25]
	v_mfma_f32_16x16x32_bf16 v[50:53], v[176:179], v[244:247], v[50:53]
	v_mfma_f32_16x16x32_bf16 v[18:21], v[190:193], v[244:247], v[18:21]
	s_setprio 0
	s_barrier
	s_add_i32 s2, s18, s22
	v_lshl_add_u64 v[180:181], v[180:181], 0, s[54:55]
	s_mov_b32 m0, s2
	ds_read_b128 v[194:197], v158 offset:49152
	ds_read_b128 v[214:217], v158 offset:50176
	ds_read_b128 v[218:221], v158 offset:51200
	ds_read_b128 v[222:225], v158 offset:52224
	ds_read_b128 v[226:229], v158 offset:53248
	ds_read_b128 v[230:233], v158 offset:54272
	ds_read_b128 v[240:243], v158 offset:55296
	ds_read_b128 v[244:247], v158 offset:56320
	global_load_lds_dwordx4 v[180:181], off
	s_add_i32 m0, s2, 0x2000
	s_add_u32 s2, s10, 0xb0080
	v_lshl_add_u64 v[180:181], v[182:183], 0, s[54:55]
	s_addc_u32 s3, s11, 0
	s_add_i32 s10, s19, s22
	global_load_lds_dwordx4 v[180:181], off
	s_waitcnt vmcnt(4)
	s_waitcnt lgkmcnt(0)
	s_barrier
	s_setprio 1
	s_waitcnt lgkmcnt(0)
	v_mfma_f32_16x16x32_bf16 v[110:113], v[152:155], v[194:197], v[110:113]
	v_mfma_f32_16x16x32_bf16 v[78:81], v[164:167], v[194:197], v[78:81]
	v_mfma_f32_16x16x32_bf16 v[106:109], v[152:155], v[218:221], v[106:109]
	v_mfma_f32_16x16x32_bf16 v[74:77], v[164:167], v[218:221], v[74:77]
	v_lshl_add_u64 v[180:181], s[2:3], 0, v[0:1]
	s_mov_b32 m0, s10
	s_nop 0
	global_load_lds_dwordx4 v[180:181], off
	v_mfma_f32_16x16x32_bf16 v[102:105], v[152:155], v[226:229], v[102:105]
	v_mfma_f32_16x16x32_bf16 v[70:73], v[164:167], v[226:229], v[70:73]
	v_mfma_f32_16x16x32_bf16 v[94:97], v[152:155], v[240:243], v[94:97]
	v_mfma_f32_16x16x32_bf16 v[62:65], v[164:167], v[240:243], v[62:65]
	v_mfma_f32_16x16x32_bf16 v[110:113], v[160:163], v[214:217], v[110:113]
	v_mfma_f32_16x16x32_bf16 v[78:81], v[168:171], v[214:217], v[78:81]
	v_mfma_f32_16x16x32_bf16 v[106:109], v[160:163], v[222:225], v[106:109]
	v_mfma_f32_16x16x32_bf16 v[74:77], v[168:171], v[222:225], v[74:77]
	v_lshl_add_u64 v[180:181], s[2:3], 0, v[130:131]
	s_add_i32 m0, s10, 0x2000
	s_nop 0
	global_load_lds_dwordx4 v[180:181], off
	v_mfma_f32_16x16x32_bf16 v[102:105], v[160:163], v[230:233], v[102:105]
	v_mfma_f32_16x16x32_bf16 v[70:73], v[168:171], v[230:233], v[70:73]
	v_mfma_f32_16x16x32_bf16 v[94:97], v[160:163], v[244:247], v[94:97]
	v_mfma_f32_16x16x32_bf16 v[62:65], v[168:171], v[244:247], v[62:65]
	s_setprio 0
	s_setprio 1
	v_mfma_f32_16x16x32_bf16 v[46:49], v[172:175], v[194:197], v[46:49]
	v_mfma_f32_16x16x32_bf16 v[14:17], v[186:189], v[194:197], v[14:17]
	v_mfma_f32_16x16x32_bf16 v[42:45], v[172:175], v[218:221], v[42:45]
	v_mfma_f32_16x16x32_bf16 v[10:13], v[186:189], v[218:221], v[10:13]
	v_lshl_add_u64 v[180:181], v[184:185], 0, s[54:55]
	s_mov_b32 m0, s31
	s_nop 0
	global_load_lds_dwordx4 v[180:181], off
	v_mfma_f32_16x16x32_bf16 v[38:41], v[172:175], v[226:229], v[38:41]
	v_mfma_f32_16x16x32_bf16 v[6:9], v[186:189], v[226:229], v[6:9]
	v_mfma_f32_16x16x32_bf16 v[30:33], v[172:175], v[240:243], v[30:33]
	v_mfma_f32_16x16x32_bf16 v[2:5], v[186:189], v[240:243], v[2:5]
	v_mfma_f32_16x16x32_bf16 v[46:49], v[176:179], v[214:217], v[46:49]
	v_mfma_f32_16x16x32_bf16 v[14:17], v[190:193], v[214:217], v[14:17]
	v_mfma_f32_16x16x32_bf16 v[42:45], v[176:179], v[222:225], v[42:45]
	v_mfma_f32_16x16x32_bf16 v[10:13], v[190:193], v[222:225], v[10:13]
	v_lshl_add_u64 v[180:181], v[210:211], 0, s[54:55]
	s_mov_b32 m0, s34
	s_nop 0
	global_load_lds_dwordx4 v[180:181], off
	v_mfma_f32_16x16x32_bf16 v[38:41], v[176:179], v[230:233], v[38:41]
	v_mfma_f32_16x16x32_bf16 v[6:9], v[190:193], v[230:233], v[6:9]
	v_mfma_f32_16x16x32_bf16 v[30:33], v[176:179], v[244:247], v[30:33]
	v_mfma_f32_16x16x32_bf16 v[2:5], v[190:193], v[244:247], v[2:5]
	s_setprio 0
	s_barrier
	s_add_i32 s40, s40, 2
	s_add_u32 s0, s0, 0x100
	s_addc_u32 s1, s1, 0
	s_cmp_gt_u32 s40, 41
	s_mov_b64 s[2:3], s[8:9]
	s_cbranch_scc0 .LBB0_1247
	s_and_b64 vcc, exec, s[46:47]
	s_cbranch_vccz .LBB0_1250
	s_barrier
